# grid barrier 2 without the L2 writeback: the only P2 output read in P3 (passA HU/HD) is stored write-through
# speedup vs baseline: 1.0086x; 1.0086x over previous
; __device__ __forceinline__ unsigned xb_add(unsigned* p, unsigned v) { return __hip_atomic_fetch_add(p, v, __ATOMIC_RELAXED, __HIP_MEMORY_SCOPE_AGENT); }
; __device__ __forceinline__ void xcd_barrier(const XcdBarrier& b) {
;     ...
;         if (old + 1u == (gen + 1u) * nloc) {
;             __builtin_amdgcn_fence(__ATOMIC_RELEASE, "agent");
;             asm volatile("s_waitcnt vmcnt(0)" ::: "memory");
;             const unsigned og = xb_add(&bar[XB_TOP], 1u);
.LBB0_610:
	s_andn2_saveexec_b64 s[2:3], s[8:9]
	s_cbranch_execz .LBB0_628
	s_mov_b64 s[2:3], exec
	s_waitcnt lgkmcnt(0)
	s_waitcnt vmcnt(0)
	v_mbcnt_lo_u32_b32 v3, s2, 0
	v_mbcnt_hi_u32_b32 v3, s3, v3
	v_cmp_eq_u32_e32 vcc, 0, v3
	s_and_saveexec_b64 s[8:9], vcc
	s_cbranch_execz .LBB0_613
	s_bcnt1_i32_b64 s2, s[2:3]
	v_mov_b32_e32 v4, 0x7000
	v_mov_b32_e32 v5, s2
	global_atomic_add v4, v4, v5, s[68:69] offset:1024 sc0
